# P3 loop: V-half LDS-DMA pair issued mid-PV instead of in the post-barrier head (head issues only the K pair)
# speedup vs baseline: 1.0017x; 1.0017x over previous
.Lk_top:
	ds_read_b128 v[80:83], v85 offset:16384
	ds_read_b128 v[202:205], v254 offset:16384
	ds_read_b128 v[194:197], v255 offset:16384
	ds_read_b128 v[186:189], v84 offset:16384
	s_cmp_ge_i32 s72, s98
	s_cbranch_scc1 .LBB0_325
	s_add_i32 m0, s1, s94
	s_add_i32 s4, s90, s1
	global_load_lds_dwordx4 v[220:221], off
	s_mov_b32 m0, s4
	s_nop 0
	global_load_lds_dwordx4 v[218:219], off

.LBB0_327:
	s_waitcnt lgkmcnt(4)
	v_mfma_f32_32x32x16_bf16 v[48:63], v[182:185], v[174:177], v[48:63]
	v_add_f32_e32 v190, v255, v80
	v_exp_f32_e32 v190, v190
	ds_read_b64_tr_b16 v[246:247], v158 offset:36864
	ds_read_b64_tr_b16 v[248:249], v158 offset:38912
	v_add_f32_e32 v157, v190, v96
	v_mfma_f32_32x32x16_bf16 v[32:47], v[178:181], v[174:177], v[32:47]
	v_add_f32_e32 v191, v255, v81
	v_exp_f32_e32 v191, v191
	ds_read_b64_tr_b16 v[250:251], v159 offset:36864
	ds_read_b64_tr_b16 v[252:253], v159 offset:38912
	v_add_f32_e32 v156, v191, v97
	v_add_f32_e32 v157, v156, v157
	s_waitcnt lgkmcnt(4)
	v_mfma_f32_32x32x16_bf16 v[16:31], v[148:151], v[174:177], v[16:31]
	v_add_f32_e32 v192, v255, v82
	v_exp_f32_e32 v192, v192
	ds_read_b64_tr_b16 v[182:183], v160 offset:36864
	ds_read_b64_tr_b16 v[184:185], v160 offset:38912
	v_add_f32_e32 v156, v192, v98
	v_add_f32_e32 v157, v156, v157
	v_mfma_f32_32x32x16_bf16 v[0:15], v[152:155], v[174:177], v[0:15]
	v_add_f32_e32 v193, v255, v83
	v_exp_f32_e32 v193, v193
	ds_read_b64_tr_b16 v[178:179], v161 offset:36864
	ds_read_b64_tr_b16 v[180:181], v161 offset:38912
	v_add_f32_e32 v156, v193, v99
	v_add_f32_e32 v157, v156, v157
	v_cvt_pk_bf16_f32 v174, v96, v97
	s_waitcnt lgkmcnt(4)
	v_mfma_f32_32x32x16_bf16 v[48:63], v[246:249], v[162:165], v[48:63]
	v_add_f32_e32 v194, v255, v84
	v_exp_f32_e32 v194, v194
	ds_read_b64_tr_b16 v[148:149], v158 offset:40960
	ds_read_b64_tr_b16 v[150:151], v158 offset:43008
	v_add_f32_e32 v156, v194, v100
	v_add_f32_e32 v157, v156, v157
	v_cvt_pk_bf16_f32 v175, v98, v99
	v_mfma_f32_32x32x16_bf16 v[32:47], v[250:253], v[162:165], v[32:47]
	v_add_f32_e32 v195, v255, v85
	v_exp_f32_e32 v195, v195
	ds_read_b64_tr_b16 v[152:153], v159 offset:40960
	ds_read_b64_tr_b16 v[154:155], v159 offset:43008
	v_add_f32_e32 v156, v195, v101
	v_add_f32_e32 v157, v156, v157
	v_cvt_pk_bf16_f32 v176, v100, v101
	s_waitcnt lgkmcnt(4)
	v_mfma_f32_32x32x16_bf16 v[16:31], v[182:185], v[162:165], v[16:31]
	s_and_b32 s4, s79, 0x18000
	s_cmp_ge_i32 s72, s98
	s_cbranch_scc1 .Lk_nov
	s_add_i32 m0, s4, s66
	s_nop 0
	global_load_lds_dwordx4 v[224:225], off
	global_load_lds_dwordx4 v[224:225], off offset:1024
.Lk_nov:
	v_add_f32_e32 v196, v255, v86
	v_exp_f32_e32 v196, v196
	ds_read_b64_tr_b16 v[246:247], v160 offset:40960
	ds_read_b64_tr_b16 v[248:249], v160 offset:43008
	v_add_f32_e32 v156, v196, v102
	v_add_f32_e32 v157, v156, v157
	v_cvt_pk_bf16_f32 v177, v102, v103
	v_mfma_f32_32x32x16_bf16 v[0:15], v[178:181], v[162:165], v[0:15]
	v_add_f32_e32 v197, v255, v87
	v_exp_f32_e32 v197, v197
	ds_read_b64_tr_b16 v[250:251], v161 offset:40960
	ds_read_b64_tr_b16 v[252:253], v161 offset:43008
	v_add_f32_e32 v156, v197, v103
	v_add_f32_e32 v157, v156, v157
	v_cvt_pk_bf16_f32 v162, v104, v105
	s_waitcnt lgkmcnt(4)
	v_mfma_f32_32x32x16_bf16 v[48:63], v[148:151], v[170:173], v[48:63]
	v_add_f32_e32 v198, v255, v88
	v_exp_f32_e32 v198, v198
	ds_read_b64_tr_b16 v[182:183], v158 offset:45056
	ds_read_b64_tr_b16 v[184:185], v158 offset:47104
	v_add_f32_e32 v156, v198, v104
	v_add_f32_e32 v157, v156, v157
	v_cvt_pk_bf16_f32 v163, v106, v107
	v_mfma_f32_32x32x16_bf16 v[32:47], v[152:155], v[170:173], v[32:47]
	v_add_f32_e32 v199, v255, v89
	v_exp_f32_e32 v199, v199
	ds_read_b64_tr_b16 v[178:179], v159 offset:45056
	ds_read_b64_tr_b16 v[180:181], v159 offset:47104
	v_add_f32_e32 v156, v199, v105
	v_add_f32_e32 v157, v156, v157
	v_cvt_pk_bf16_f32 v164, v108, v109
	s_waitcnt lgkmcnt(4)
	v_mfma_f32_32x32x16_bf16 v[16:31], v[246:249], v[170:173], v[16:31]
	v_add_f32_e32 v200, v255, v90
	v_exp_f32_e32 v200, v200
	ds_read_b64_tr_b16 v[148:149], v160 offset:45056
	ds_read_b64_tr_b16 v[150:151], v160 offset:47104
	v_add_f32_e32 v156, v200, v106
	v_add_f32_e32 v157, v156, v157
	v_cvt_pk_bf16_f32 v165, v110, v111
	v_mfma_f32_32x32x16_bf16 v[0:15], v[250:253], v[170:173], v[0:15]
	v_add_f32_e32 v201, v255, v91
	v_exp_f32_e32 v201, v201
	ds_read_b64_tr_b16 v[152:153], v161 offset:45056
	ds_read_b64_tr_b16 v[154:155], v161 offset:47104
	v_add_f32_e32 v156, v201, v107
	v_add_f32_e32 v157, v156, v157
	v_cvt_pk_bf16_f32 v170, v190, v191
	s_waitcnt lgkmcnt(4)
	v_mfma_f32_32x32x16_bf16 v[48:63], v[182:185], v[166:169], v[48:63]
	v_add_f32_e32 v202, v255, v92
	v_exp_f32_e32 v202, v202
	v_cvt_pk_bf16_f32 v171, v192, v193
	v_add_f32_e32 v156, v202, v108
	v_add_f32_e32 v157, v156, v157
	v_mfma_f32_32x32x16_bf16 v[32:47], v[178:181], v[166:169], v[32:47]
	v_add_f32_e32 v203, v255, v93
	v_exp_f32_e32 v203, v203
	v_cvt_pk_bf16_f32 v172, v194, v195
	v_add_f32_e32 v156, v203, v109
	v_add_f32_e32 v157, v156, v157
	s_waitcnt lgkmcnt(0)
	v_mfma_f32_32x32x16_bf16 v[16:31], v[148:151], v[166:169], v[16:31]
	v_add_f32_e32 v204, v255, v94
	v_exp_f32_e32 v204, v204
	v_cvt_pk_bf16_f32 v173, v196, v197
	v_add_f32_e32 v156, v204, v110
	v_add_f32_e32 v157, v156, v157
	v_mfma_f32_32x32x16_bf16 v[0:15], v[152:155], v[166:169], v[0:15]
	v_add_f32_e32 v205, v255, v95
	v_exp_f32_e32 v205, v205
	v_cvt_pk_bf16_f32 v166, v198, v199
	v_add_f32_e32 v156, v205, v111
	v_add_f32_e32 v157, v156, v157
	v_cvt_pk_bf16_f32 v167, v200, v201
	v_cvt_pk_bf16_f32 v168, v202, v203
	v_cvt_pk_bf16_f32 v169, v204, v205
	s_add_i32 s72, s72, 1
	s_add_i32 s79, s79, 0x8000
	s_add_i32 s100, s100, 64
	v_add_f32_e32 v229, v229, v157
	v_lshl_add_u64 v[218:219], v[218:219], 0, s[88:89]
	v_lshl_add_u64 v[220:221], v[220:221], 0, s[88:89]
	v_lshl_add_u64 v[224:225], v[224:225], 0, s[92:93]
	s_and_b32 s1, s79, 0x18000
	s_xor_b32 s0, s1, 0x10000
	v_add_u32_e32 v85, s0, v222
	v_add_u32_e32 v254, s0, v223
	v_add_u32_e32 v255, s0, v241
	v_add_u32_e32 v84, s0, v242
	s_cmp_ge_i32 s72, s99
	s_cbranch_scc1 .LBB0_332
	s_cmp_ge_i32 s72, s73
	s_cbranch_scc1 .Lk_last
	s_waitcnt vmcnt(4) lgkmcnt(0)
	s_barrier
	s_branch .Lk_top
